# step 4/5: waves 4-7 pass the step-4 workgroup barrier before their qk epilogue, so the kk epilogue runs alone on its SIMDs and the qk epilogue overlaps the solve
# baseline (speedup 1.0000x reference)
.LBB0_137:
	s_waitcnt lgkmcnt(0)
	s_barrier
	v_lshl_or_b32 v21, s6, 5, v94
	v_lshl_or_b32 v22, s52, 5, v25
	v_lshl_add_u32 v18, v21, 2, 0
	v_lshl_add_u32 v19, v22, 2, 0
	v_add_u32_e32 v18, 0x24900, v18
	v_add_u32_e32 v19, 0x24900, v19
	ds_read_b32 v20, v18
	ds_read_b128 v[106:109], v19
	ds_read_b128 v[110:113], v19 offset:32
	ds_read_b128 v[114:117], v19 offset:64
	ds_read_b128 v[118:121], v19 offset:96
	v_sub_u32_e32 v21, v21, v22
	v_add_u32_e32 v21, 1, v21
	s_lshl_b32 s6, s6, 12
	s_lshl_b32 s7, s52, 11
	s_or_b32 s6, s6, s7
	v_lshl_or_b32 v22, v93, 4, s6
	s_add_i32 s6, s51, 0x8000
	v_add_u32_e32 v18, s6, v22
	s_add_i32 s6, s51, 0x8400
	v_add_u32_e32 v22, s6, v22
	s_waitcnt lgkmcnt(0)
	v_sub_f32_e32 v106, v20, v106
	v_sub_f32_e32 v107, v20, v107
	v_sub_f32_e32 v108, v20, v108
	v_sub_f32_e32 v109, v20, v109
	v_sub_f32_e32 v110, v20, v110
	v_sub_f32_e32 v111, v20, v111
	v_sub_f32_e32 v112, v20, v112
	v_sub_f32_e32 v113, v20, v113
	v_sub_f32_e32 v114, v20, v114
	v_sub_f32_e32 v115, v20, v115
	v_sub_f32_e32 v116, v20, v116
	v_sub_f32_e32 v117, v20, v117
	v_sub_f32_e32 v118, v20, v118
	v_sub_f32_e32 v119, v20, v119
	v_sub_f32_e32 v120, v20, v120
	v_sub_f32_e32 v121, v20, v121
	v_mul_f32_e32 v106, 0x3fb8aa3b, v106
	v_mul_f32_e32 v107, 0x3fb8aa3b, v107
	v_mul_f32_e32 v108, 0x3fb8aa3b, v108
	v_mul_f32_e32 v109, 0x3fb8aa3b, v109
	v_mul_f32_e32 v110, 0x3fb8aa3b, v110
	v_mul_f32_e32 v111, 0x3fb8aa3b, v111
	v_mul_f32_e32 v112, 0x3fb8aa3b, v112
	v_mul_f32_e32 v113, 0x3fb8aa3b, v113
	v_mul_f32_e32 v114, 0x3fb8aa3b, v114
	v_mul_f32_e32 v115, 0x3fb8aa3b, v115
	v_mul_f32_e32 v116, 0x3fb8aa3b, v116
	v_mul_f32_e32 v117, 0x3fb8aa3b, v117
	v_mul_f32_e32 v118, 0x3fb8aa3b, v118
	v_mul_f32_e32 v119, 0x3fb8aa3b, v119
	v_mul_f32_e32 v120, 0x3fb8aa3b, v120
	v_mul_f32_e32 v121, 0x3fb8aa3b, v121
	v_exp_f32_e32 v106, v106
	v_exp_f32_e32 v107, v107
	v_exp_f32_e32 v108, v108
	v_exp_f32_e32 v109, v109
	v_exp_f32_e32 v110, v110
	v_exp_f32_e32 v111, v111
	v_exp_f32_e32 v112, v112
	v_exp_f32_e32 v113, v113
	v_exp_f32_e32 v114, v114
	v_exp_f32_e32 v115, v115
	v_exp_f32_e32 v116, v116
	v_exp_f32_e32 v117, v117
	v_exp_f32_e32 v118, v118
	v_exp_f32_e32 v119, v119
	v_exp_f32_e32 v120, v120
	v_exp_f32_e32 v121, v121
	v_mul_f32_e32 v106, v2, v106
	v_mul_f32_e32 v107, v3, v107
	v_mul_f32_e32 v108, v4, v108
	v_mul_f32_e32 v109, v5, v109
	v_mul_f32_e32 v110, v6, v110
	v_mul_f32_e32 v111, v7, v111
	v_mul_f32_e32 v112, v8, v112
	v_mul_f32_e32 v113, v9, v113
	v_mul_f32_e32 v114, v10, v114
	v_mul_f32_e32 v115, v11, v115
	v_mul_f32_e32 v116, v12, v116
	v_mul_f32_e32 v117, v13, v117
	v_mul_f32_e32 v118, v14, v118
	v_mul_f32_e32 v119, v15, v119
	v_mul_f32_e32 v120, v16, v120
	v_mul_f32_e32 v121, v17, v121
	v_cmp_lt_i32_e32 vcc, 0, v21
	v_cmp_lt_i32_e64 s[28:29], 1, v21
	v_cmp_lt_i32_e64 s[6:7], 2, v21
	v_cndmask_b32_e32 v106, 0, v106, vcc
	v_cmp_lt_i32_e32 vcc, 3, v21
	v_cndmask_b32_e64 v107, 0, v107, s[28:29]
	v_cmp_lt_i32_e64 s[28:29], 8, v21
	v_cndmask_b32_e64 v108, 0, v108, s[6:7]
	v_cmp_lt_i32_e64 s[6:7], 9, v21
	v_cndmask_b32_e32 v109, 0, v109, vcc
	v_cmp_lt_i32_e32 vcc, 10, v21
	v_cndmask_b32_e64 v110, 0, v110, s[28:29]
	v_cmp_lt_i32_e64 s[28:29], 11, v21
	v_cndmask_b32_e64 v111, 0, v111, s[6:7]
	v_cmp_lt_i32_e64 s[6:7], 16, v21
	v_cndmask_b32_e32 v112, 0, v112, vcc
	v_cmp_lt_i32_e32 vcc, 17, v21
	v_cndmask_b32_e64 v113, 0, v113, s[28:29]
	v_cmp_lt_i32_e64 s[28:29], 18, v21
	v_cndmask_b32_e64 v114, 0, v114, s[6:7]
	v_cmp_lt_i32_e64 s[6:7], 19, v21
	v_cndmask_b32_e32 v115, 0, v115, vcc
	v_cmp_lt_i32_e32 vcc, 24, v21
	v_cndmask_b32_e64 v116, 0, v116, s[28:29]
	v_cmp_lt_i32_e64 s[28:29], 25, v21
	v_cndmask_b32_e64 v117, 0, v117, s[6:7]
	v_cmp_lt_i32_e64 s[6:7], 26, v21
	v_cndmask_b32_e32 v118, 0, v118, vcc
	v_cmp_lt_i32_e32 vcc, 27, v21
	v_cndmask_b32_e64 v119, 0, v119, s[28:29]
	v_cndmask_b32_e64 v120, 0, v120, s[6:7]
	v_cndmask_b32_e32 v121, 0, v121, vcc
	v_cvt_pk_bf16_f32 v122, v106, v107
	v_cvt_pk_bf16_f32 v123, v108, v109
	v_cvt_pk_bf16_f32 v124, v110, v111
	v_cvt_pk_bf16_f32 v125, v112, v113
	v_cvt_pk_bf16_f32 v126, v114, v115
	v_cvt_pk_bf16_f32 v127, v116, v117
	v_cvt_pk_bf16_f32 v128, v118, v119
	v_cvt_pk_bf16_f32 v129, v120, v121
	buffer_store_dwordx4 v[122:125], v18, s[72:75], 0 offen sc1
	buffer_store_dwordx4 v[126:129], v22, s[72:75], 0 offen sc1
	v_lshl_or_b32 v96, s52, 5, v94
	s_branch .Lqk_after

.Lqk_after:
	s_andn2_b64 vcc, exec, s[94:95]
	s_cbranch_vccnz .LBB0_206
	s_waitcnt vmcnt(2)
